# adds diff-attention epilogue loading the 8 sub-LN gain vectors once (15 serialized loads and vmcnt(0) drains removed) on top of previous version
# speedup vs baseline: 1.0339x; 1.0006x over previous
; DI void diff_attn_item(const PRef& p, int l, int b, int h, int qt) {
;     ...
;     float a1 = ((const float*)p.in[I_LQ1])[l * 64 + lane] * ((const float*)p.in[I_LK1])[l * 64 + lane];
;     float a2 = ((const float*)p.in[I_LQ2])[l * 64 + lane] * ((const float*)p.in[I_LK2])[l * 64 + lane];
;     a1 = wave_sum(a1); a2 = wave_sum(a2);
;     lam = __expf(a1) - __expf(a2) + p.lam_init[l];
;     ...
;     for (int qb = 0; qb < 2; ++qb) {
;       float ss = 0.f;
; #pragma unroll
;       for (int d = 0; d < 8; ++d) {
;         float4 c2 = *reinterpret_cast<const float4*>(&comb[(qsub * 32 + qb * 16 + fr) * 132 + d * 16 + fq * 4]);
;         fw.o[qb][d][0] = fw.o[qb][d][0] * inv[qb] - lam * c2.x;
;         fw.o[qb][d][1] = fw.o[qb][d][1] * inv[qb] - lam * c2.y;
;         fw.o[qb][d][2] = fw.o[qb][d][2] * inv[qb] - lam * c2.z;
;         fw.o[qb][d][3] = fw.o[qb][d][3] * inv[qb] - lam * c2.w;
;         for (int j = 0; j < 4; ++j) ss += fw.o[qb][d][j] * fw.o[qb][d][j];
;       }
;       ss += __shfl_xor(ss, 16); ss += __shfl_xor(ss, 32);
;       const float rms = rsqrtf(ss * (1.f / 128.f) + 1e-6f) * post;
.LBB0_212:
	s_or_b64 exec, exec, s[6:7]
	v_cmp_gt_u32_e32 vcc, s49, v188
	s_waitcnt lgkmcnt(0)
	s_barrier
	s_and_saveexec_b64 s[6:7], vcc
	s_cbranch_execz .LBB0_214
	v_mov_b32_e32 v37, s29
	v_mov_b32_e32 v40, s15
	v_add_f32_e32 v37, s28, v37
	v_add_f32_e32 v40, s14, v40
	v_mov_b32_e32 v38, s31
	v_add_f32_e32 v37, v40, v37
	v_mov_b32_e32 v40, s8
	v_add_f32_e32 v38, s30, v38
	v_add_f32_e32 v40, s27, v40
	v_add_f32_e32 v38, v40, v38
	v_mul_f32_e32 v37, 0x3fb8aa3b, v37
	v_mul_f32_e32 v38, 0x3fb8aa3b, v38
	v_exp_f32_e32 v37, v37
	v_exp_f32_e32 v38, v38
	v_lshl_or_b32 v44, v189, 5, v187
	s_movk_i32 s11, 0x210
	s_load_dwordx2 s[8:9], s[18:19], 0x40
	v_sub_f32_e32 v37, v37, v38
	v_mul_lo_u32 v38, v44, s11
	v_add3_u32 v110, 16, v16, v38
	s_waitcnt vmcnt(3)
	ds_read_b128 v[50:53], v110 offset:36864
	s_waitcnt vmcnt(2)
	ds_read_b128 v[54:57], v110 offset:36928
	v_add_f32_e32 v38, s10, v37
	s_waitcnt lgkmcnt(0)
	s_add_u32 s8, s8, s24
	s_addc_u32 s9, s9, 0
	v_lshlrev_b32_e32 v45, 4, v186
	v_pk_mul_f32 v[52:53], v[38:39], v[52:53] op_sel_hi:[0,1]
	v_pk_mul_f32 v[50:51], v[38:39], v[50:51] op_sel_hi:[0,1]
	v_pk_fma_f32 v[68:69], v[68:69], v[36:37], v[52:53] op_sel_hi:[1,0,1] neg_lo:[0,0,1] neg_hi:[0,0,1]
	v_pk_fma_f32 v[66:67], v[66:67], v[36:37], v[50:51] op_sel_hi:[1,0,1] neg_lo:[0,0,1] neg_hi:[0,0,1]
	global_load_dwordx4 v[50:53], v45, s[8:9]
	global_load_dwordx4 v[120:123], v45, s[8:9]
	global_load_dwordx4 v[124:127], v45, s[8:9] offset:64
	global_load_dwordx4 v[128:131], v45, s[8:9] offset:128
	global_load_dwordx4 v[132:135], v45, s[8:9] offset:192
	global_load_dwordx4 v[136:139], v45, s[8:9] offset:256
	global_load_dwordx4 v[140:143], v45, s[8:9] offset:320
	global_load_dwordx4 v[144:147], v45, s[8:9] offset:384
	global_load_dwordx4 v[148:151], v45, s[8:9] offset:448
	ds_read_b128 v[40:43], v110 offset:37312
	ds_read_b128 v[46:49], v110 offset:37248
	v_pk_mul_f32 v[56:57], v[38:39], v[56:57] op_sel_hi:[0,1]
	v_pk_fma_f32 v[72:73], v[72:73], v[36:37], v[56:57] op_sel_hi:[1,0,1] neg_lo:[0,0,1] neg_hi:[0,0,1]
	s_waitcnt vmcnt(10)
	ds_read_b128 v[56:59], v110 offset:36992
	s_waitcnt vmcnt(9)
	ds_read_b128 v[60:63], v110 offset:37056
	s_waitcnt lgkmcnt(3)
	v_pk_mul_f32 v[42:43], v[38:39], v[42:43] op_sel_hi:[0,1]
	v_pk_mul_f32 v[98:99], v[66:67], v[66:67]
	v_pk_fma_f32 v[42:43], v[96:97], v[36:37], v[42:43] op_sel_hi:[1,0,1] neg_lo:[0,0,1] neg_hi:[0,0,1]
	v_pk_mul_f32 v[96:97], v[68:69], v[68:69]
	v_pk_mul_f32 v[54:55], v[38:39], v[54:55] op_sel_hi:[0,1]
	v_add_f32_e32 v16, v98, v99
	v_pk_fma_f32 v[70:71], v[70:71], v[36:37], v[54:55] op_sel_hi:[1,0,1] neg_lo:[0,0,1] neg_hi:[0,0,1]
	v_add_f32_e32 v16, v16, v96
	v_pk_mul_f32 v[102:103], v[70:71], v[70:71]
	v_add_f32_e32 v16, v16, v97
	s_waitcnt lgkmcnt(1)
	v_pk_mul_f32 v[54:55], v[38:39], v[58:59] op_sel_hi:[0,1]
	v_add_f32_e32 v16, v16, v102
	v_pk_mul_f32 v[100:101], v[72:73], v[72:73]
	v_pk_fma_f32 v[76:77], v[76:77], v[36:37], v[54:55] op_sel_hi:[1,0,1] neg_lo:[0,0,1] neg_hi:[0,0,1]
	v_pk_mul_f32 v[54:55], v[38:39], v[56:57] op_sel_hi:[0,1]
	v_add_f32_e32 v16, v16, v103
	v_pk_fma_f32 v[74:75], v[74:75], v[36:37], v[54:55] op_sel_hi:[1,0,1] neg_lo:[0,0,1] neg_hi:[0,0,1]
	v_add_f32_e32 v16, v16, v100
	v_pk_mul_f32 v[106:107], v[74:75], v[74:75]
	s_waitcnt lgkmcnt(0)
	v_pk_mul_f32 v[54:55], v[38:39], v[62:63] op_sel_hi:[0,1]
	v_add_f32_e32 v16, v16, v101
	v_pk_fma_f32 v[62:63], v[80:81], v[36:37], v[54:55] op_sel_hi:[1,0,1] neg_lo:[0,0,1] neg_hi:[0,0,1]
	ds_read_b128 v[54:57], v110 offset:37120
	v_add_f32_e32 v16, v16, v106
	v_pk_mul_f32 v[104:105], v[76:77], v[76:77]
	v_pk_mul_f32 v[58:59], v[38:39], v[60:61] op_sel_hi:[0,1]
	v_add_f32_e32 v16, v16, v107
	v_pk_fma_f32 v[78:79], v[78:79], v[36:37], v[58:59] op_sel_hi:[1,0,1] neg_lo:[0,0,1] neg_hi:[0,0,1]
	v_add_f32_e32 v16, v16, v104
	v_pk_mul_f32 v[108:109], v[78:79], v[78:79]
	v_add_f32_e32 v16, v16, v105
	ds_read_b128 v[58:61], v110 offset:37184
	v_add_f32_e32 v16, v16, v108
	v_pk_mul_f32 v[80:81], v[62:63], v[62:63]
	s_waitcnt lgkmcnt(1)
	v_pk_mul_f32 v[54:55], v[38:39], v[54:55] op_sel_hi:[0,1]
	v_add_f32_e32 v16, v16, v109
	v_pk_fma_f32 v[54:55], v[82:83], v[36:37], v[54:55] op_sel_hi:[1,0,1] neg_lo:[0,0,1] neg_hi:[0,0,1]
	v_add_f32_e32 v16, v16, v80
	v_pk_mul_f32 v[56:57], v[38:39], v[56:57] op_sel_hi:[0,1]
	v_pk_mul_f32 v[82:83], v[54:55], v[54:55]
	v_add_f32_e32 v16, v16, v81
	v_pk_fma_f32 v[56:57], v[84:85], v[36:37], v[56:57] op_sel_hi:[1,0,1] neg_lo:[0,0,1] neg_hi:[0,0,1]
	v_add_f32_e32 v16, v16, v82
	v_pk_mul_f32 v[84:85], v[56:57], v[56:57]
	s_waitcnt lgkmcnt(0)
	v_pk_mul_f32 v[58:59], v[38:39], v[58:59] op_sel_hi:[0,1]
	v_add_f32_e32 v16, v16, v83
	v_pk_fma_f32 v[58:59], v[90:91], v[36:37], v[58:59] op_sel_hi:[1,0,1] neg_lo:[0,0,1] neg_hi:[0,0,1]
	v_add_f32_e32 v16, v16, v84
	v_pk_mul_f32 v[60:61], v[38:39], v[60:61] op_sel_hi:[0,1]
	v_pk_mul_f32 v[90:91], v[58:59], v[58:59]
	v_add_f32_e32 v16, v16, v85
	v_pk_fma_f32 v[60:61], v[92:93], v[36:37], v[60:61] op_sel_hi:[1,0,1] neg_lo:[0,0,1] neg_hi:[0,0,1]
	v_add_f32_e32 v16, v16, v90
	v_pk_mul_f32 v[92:93], v[60:61], v[60:61]
	v_pk_mul_f32 v[46:47], v[38:39], v[46:47] op_sel_hi:[0,1]
	v_add_f32_e32 v16, v16, v91
	v_pk_mul_f32 v[40:41], v[38:39], v[40:41] op_sel_hi:[0,1]
	v_pk_mul_f32 v[48:49], v[38:39], v[48:49] op_sel_hi:[0,1]
	v_pk_fma_f32 v[86:87], v[86:87], v[36:37], v[46:47] op_sel_hi:[1,0,1] neg_lo:[0,0,1] neg_hi:[0,0,1]
	v_add_f32_e32 v16, v16, v92
	v_pk_fma_f32 v[40:41], v[94:95], v[36:37], v[40:41] op_sel_hi:[1,0,1] neg_lo:[0,0,1] neg_hi:[0,0,1]
	v_pk_fma_f32 v[88:89], v[88:89], v[36:37], v[48:49] op_sel_hi:[1,0,1] neg_lo:[0,0,1] neg_hi:[0,0,1]
	v_pk_mul_f32 v[36:37], v[86:87], v[86:87]
	v_add_f32_e32 v16, v16, v93
	v_add_f32_e32 v16, v16, v36
	v_pk_mul_f32 v[48:49], v[88:89], v[88:89]
	v_add_f32_e32 v16, v16, v37
	v_add_f32_e32 v16, v16, v48
	v_pk_mul_f32 v[64:65], v[40:41], v[40:41]
	v_add_f32_e32 v16, v16, v49
	v_add_f32_e32 v16, v16, v64
	v_pk_mul_f32 v[94:95], v[42:43], v[42:43]
	v_add_f32_e32 v16, v16, v65
	v_add_f32_e32 v16, v16, v94
	v_add_f32_e32 v16, v16, v95
	ds_bpermute_b32 v36, v35, v16
	v_or_b32_e32 v37, s12, v44
	v_sub_f32_e64 v84, 1.0, s10
	s_lshl_b32 s10, s13, 1
	s_add_u32 s2, s2, s10
	s_waitcnt lgkmcnt(0)
; DI unsigned pack2(float a, float b) { f32v2 v = {a, b}; return __builtin_bit_cast(unsigned, __builtin_convertvector(v, bf16v2)); }
; DI void diff_attn_item(const PRef& p, int l, int b, int h, int qt) {
;     ...
;       ss += __shfl_xor(ss, 16); ss += __shfl_xor(ss, 32);
;       const float rms = rsqrtf(ss * (1.f / 128.f) + 1e-6f) * post;
;       u16* op = hcat + (size_t)(tok0 + qsub * 32 + qb * 16 + fr) * 1024 + h * 128;
; #pragma unroll
;       for (int d = 0; d < 8; ++d) {
;         const int dv = d * 16 + fq * 4;
;         uint2 ov;
;         ov.x = pack2(fw.o[qb][d][0] * rms * sg[dv], fw.o[qb][d][1] * rms * sg[dv + 1]);
;         ov.y = pack2(fw.o[qb][d][2] * rms * sg[dv + 2], fw.o[qb][d][3] * rms * sg[dv + 3]);
;         *reinterpret_cast<uint2*>(op + dv) = ov;
	v_add_f32_e32 v36, v16, v36
	ds_bpermute_b32 v44, v39, v36
	v_lshlrev_b32_e32 v16, 11, v37
	s_addc_u32 s3, s3, 0
	s_waitcnt lgkmcnt(0)
	v_add_f32_e32 v36, v36, v44
	v_fmamk_f32 v36, v36, 0x3c000000, v241
	v_mul_f32_e32 v37, 0x4b800000, v36
	v_cmp_gt_f32_e32 vcc, s46, v36
	s_nop 1
	v_cndmask_b32_e32 v36, v36, v37, vcc
	v_rsq_f32_e32 v44, v36
	v_lshl_add_u64 v[36:37], s[2:3], 0, v[16:17]
	v_lshlrev_b32_e32 v16, 3, v186
	v_lshl_add_u64 v[64:65], v[36:37], 0, v[16:17]
	v_mul_f32_e32 v46, 0x45800000, v44
	v_cndmask_b32_e32 v44, v44, v46, vcc
	v_mul_f32_e32 v44, v84, v44
	v_pk_mul_f32 v[46:47], v[66:67], v[44:45] op_sel_hi:[1,0]
	v_pk_mul_f32 v[48:49], v[68:69], v[44:45] op_sel_hi:[1,0]
	s_waitcnt vmcnt(0)
	v_pk_mul_f32 v[46:47], v[50:51], v[46:47]
	v_pk_mul_f32 v[48:49], v[52:53], v[48:49]
	s_mov_b32 s2, 0x12000000
	v_cvt_pk_bf16_f32 v46, v46, v47
	v_cvt_pk_bf16_f32 v47, v48, v49
	v_add_co_u32_e32 v48, vcc, s2, v64
	v_pk_mul_f32 v[50:51], v[70:71], v[44:45] op_sel_hi:[1,0]
	s_nop 0
	v_addc_co_u32_e32 v49, vcc, 0, v65, vcc
	global_store_dwordx2 v[48:49], v[46:47], off
	v_pk_mul_f32 v[52:53], v[72:73], v[44:45] op_sel_hi:[1,0]
	s_mov_b64 s[2:3], 0x12000000
	v_lshl_add_u64 v[82:83], v[64:65], 0, s[2:3]
	s_mov_b64 s[2:3], 0x12008000
	v_pk_mul_f32 v[46:47], v[124:125], v[50:51]
	v_pk_mul_f32 v[48:49], v[126:127], v[52:53]
	v_cvt_pk_bf16_f32 v46, v46, v47
	v_cvt_pk_bf16_f32 v47, v48, v49
	global_store_dwordx2 v[82:83], v[46:47], off offset:32
	v_pk_mul_f32 v[50:51], v[74:75], v[44:45] op_sel_hi:[1,0]
	v_pk_mul_f32 v[52:53], v[76:77], v[44:45] op_sel_hi:[1,0]
	v_pk_mul_f32 v[46:47], v[128:129], v[50:51]
	v_pk_mul_f32 v[48:49], v[52:53], v[130:131]
	v_cvt_pk_bf16_f32 v46, v46, v47
	v_cvt_pk_bf16_f32 v47, v48, v49
	global_store_dwordx2 v[82:83], v[46:47], off offset:64
	v_pk_mul_f32 v[50:51], v[78:79], v[44:45] op_sel_hi:[1,0]
	v_pk_mul_f32 v[52:53], v[62:63], v[44:45] op_sel_hi:[1,0]
	v_pk_mul_f32 v[46:47], v[50:51], v[132:133]
	v_pk_mul_f32 v[48:49], v[52:53], v[134:135]
	v_cvt_pk_bf16_f32 v46, v46, v47
	v_cvt_pk_bf16_f32 v47, v48, v49
	global_store_dwordx2 v[82:83], v[46:47], off offset:96
	v_pk_mul_f32 v[50:51], v[54:55], v[44:45] op_sel_hi:[1,0]
	v_pk_mul_f32 v[52:53], v[56:57], v[44:45] op_sel_hi:[1,0]
	v_pk_mul_f32 v[46:47], v[50:51], v[136:137]
	v_pk_mul_f32 v[48:49], v[52:53], v[138:139]
	v_cvt_pk_bf16_f32 v46, v46, v47
	v_cvt_pk_bf16_f32 v47, v48, v49
	global_store_dwordx2 v[82:83], v[46:47], off offset:128
	v_pk_mul_f32 v[50:51], v[58:59], v[44:45] op_sel_hi:[1,0]
	v_pk_mul_f32 v[52:53], v[60:61], v[44:45] op_sel_hi:[1,0]
	v_pk_mul_f32 v[46:47], v[50:51], v[140:141]
	v_pk_mul_f32 v[48:49], v[52:53], v[142:143]
	v_cvt_pk_bf16_f32 v46, v46, v47
	v_cvt_pk_bf16_f32 v47, v48, v49
	global_store_dwordx2 v[82:83], v[46:47], off offset:160
	v_pk_mul_f32 v[50:51], v[86:87], v[44:45] op_sel_hi:[1,0]
	v_pk_mul_f32 v[52:53], v[88:89], v[44:45] op_sel_hi:[1,0]
	v_pk_mul_f32 v[46:47], v[50:51], v[144:145]
	v_pk_mul_f32 v[48:49], v[52:53], v[146:147]
	v_cvt_pk_bf16_f32 v46, v46, v47
	v_cvt_pk_bf16_f32 v47, v48, v49
	global_store_dwordx2 v[82:83], v[46:47], off offset:192
	ds_read_b128 v[50:53], v110 offset:45760
	ds_read_b128 v[54:57], v110 offset:45312
	ds_read_b128 v[58:61], v110 offset:45376
	ds_read_b128 v[62:65], v110 offset:45440
	ds_read_b128 v[66:69], v110 offset:45504
	ds_read_b128 v[70:73], v110 offset:45568
	ds_read_b128 v[74:77], v110 offset:45632
	ds_read_b128 v[78:81], v110 offset:45696
	s_waitcnt lgkmcnt(7)
	v_pk_mul_f32 v[50:51], v[38:39], v[50:51] op_sel_hi:[0,1]
	v_pk_mul_f32 v[52:53], v[38:39], v[52:53] op_sel_hi:[0,1]
	s_waitcnt lgkmcnt(6)
	v_pk_mul_f32 v[56:57], v[38:39], v[56:57] op_sel_hi:[0,1]
	v_pk_mul_f32 v[54:55], v[38:39], v[54:55] op_sel_hi:[0,1]
	v_pk_fma_f32 v[30:31], v[30:31], v[34:35], v[50:51] op_sel_hi:[1,0,1] neg_lo:[0,0,1] neg_hi:[0,0,1]
	v_pk_fma_f32 v[32:33], v[32:33], v[34:35], v[52:53] op_sel_hi:[1,0,1] neg_lo:[0,0,1] neg_hi:[0,0,1]
	v_pk_fma_f32 v[50:51], v[2:3], v[34:35], v[56:57] op_sel_hi:[1,0,1] neg_lo:[0,0,1] neg_hi:[0,0,1]
	v_pk_fma_f32 v[52:53], v[0:1], v[34:35], v[54:55] op_sel_hi:[1,0,1] neg_lo:[0,0,1] neg_hi:[0,0,1]
	v_pk_mul_f32 v[0:1], v[40:41], v[44:45] op_sel_hi:[1,0]
	v_pk_mul_f32 v[2:3], v[42:43], v[44:45] op_sel_hi:[1,0]
	s_waitcnt lgkmcnt(5)
	v_pk_mul_f32 v[60:61], v[38:39], v[60:61] op_sel_hi:[0,1]
	v_pk_mul_f32 v[58:59], v[38:39], v[58:59] op_sel_hi:[0,1]
	s_waitcnt lgkmcnt(4)
	v_pk_mul_f32 v[64:65], v[38:39], v[64:65] op_sel_hi:[0,1]
	v_pk_mul_f32 v[62:63], v[38:39], v[62:63] op_sel_hi:[0,1]
	s_waitcnt lgkmcnt(3)
	v_pk_mul_f32 v[68:69], v[38:39], v[68:69] op_sel_hi:[0,1]
	v_pk_mul_f32 v[66:67], v[38:39], v[66:67] op_sel_hi:[0,1]
	s_waitcnt lgkmcnt(2)
	v_pk_mul_f32 v[72:73], v[38:39], v[72:73] op_sel_hi:[0,1]
	v_pk_mul_f32 v[70:71], v[38:39], v[70:71] op_sel_hi:[0,1]
	s_waitcnt lgkmcnt(1)
	v_pk_mul_f32 v[76:77], v[38:39], v[76:77] op_sel_hi:[0,1]
	v_pk_mul_f32 v[74:75], v[38:39], v[74:75] op_sel_hi:[0,1]
	s_waitcnt lgkmcnt(0)
; DI unsigned pack2(float a, float b) { f32v2 v = {a, b}; return __builtin_bit_cast(unsigned, __builtin_convertvector(v, bf16v2)); }
; DI void diff_attn_item(const PRef& p, int l, int b, int h, int qt) {
;     ...
;     for (int qb = 0; qb < 2; ++qb) {
;       float ss = 0.f;
; #pragma unroll
;       for (int d = 0; d < 8; ++d) {
;         float4 c2 = *reinterpret_cast<const float4*>(&comb[(qsub * 32 + qb * 16 + fr) * 132 + d * 16 + fq * 4]);
;         fw.o[qb][d][0] = fw.o[qb][d][0] * inv[qb] - lam * c2.x;
;         fw.o[qb][d][1] = fw.o[qb][d][1] * inv[qb] - lam * c2.y;
;         fw.o[qb][d][2] = fw.o[qb][d][2] * inv[qb] - lam * c2.z;
;         fw.o[qb][d][3] = fw.o[qb][d][3] * inv[qb] - lam * c2.w;
;         for (int j = 0; j < 4; ++j) ss += fw.o[qb][d][j] * fw.o[qb][d][j];
;       }
;       ss += __shfl_xor(ss, 16); ss += __shfl_xor(ss, 32);
;       const float rms = rsqrtf(ss * (1.f / 128.f) + 1e-6f) * post;
;       u16* op = hcat + (size_t)(tok0 + qsub * 32 + qb * 16 + fr) * 1024 + h * 128;
; #pragma unroll
;       for (int d = 0; d < 8; ++d) {
;         const int dv = d * 16 + fq * 4;
;         uint2 ov;
;         ov.x = pack2(fw.o[qb][d][0] * rms * sg[dv], fw.o[qb][d][1] * rms * sg[dv + 1]);
;         ov.y = pack2(fw.o[qb][d][2] * rms * sg[dv + 2], fw.o[qb][d][3] * rms * sg[dv + 3]);
;         *reinterpret_cast<uint2*>(op + dv) = ov;
	v_pk_mul_f32 v[80:81], v[38:39], v[80:81] op_sel_hi:[0,1]
	v_pk_mul_f32 v[78:79], v[38:39], v[78:79] op_sel_hi:[0,1]
	v_pk_fma_f32 v[20:21], v[20:21], v[34:35], v[60:61] op_sel_hi:[1,0,1] neg_lo:[0,0,1] neg_hi:[0,0,1]
	v_pk_fma_f32 v[18:19], v[18:19], v[34:35], v[58:59] op_sel_hi:[1,0,1] neg_lo:[0,0,1] neg_hi:[0,0,1]
	v_pk_fma_f32 v[24:25], v[24:25], v[34:35], v[64:65] op_sel_hi:[1,0,1] neg_lo:[0,0,1] neg_hi:[0,0,1]
	v_pk_fma_f32 v[22:23], v[22:23], v[34:35], v[62:63] op_sel_hi:[1,0,1] neg_lo:[0,0,1] neg_hi:[0,0,1]
	v_pk_fma_f32 v[14:15], v[14:15], v[34:35], v[68:69] op_sel_hi:[1,0,1] neg_lo:[0,0,1] neg_hi:[0,0,1]
	v_pk_fma_f32 v[12:13], v[12:13], v[34:35], v[66:67] op_sel_hi:[1,0,1] neg_lo:[0,0,1] neg_hi:[0,0,1]
	v_pk_fma_f32 v[10:11], v[10:11], v[34:35], v[72:73] op_sel_hi:[1,0,1] neg_lo:[0,0,1] neg_hi:[0,0,1]
	v_pk_fma_f32 v[8:9], v[8:9], v[34:35], v[70:71] op_sel_hi:[1,0,1] neg_lo:[0,0,1] neg_hi:[0,0,1]
	v_pk_fma_f32 v[6:7], v[6:7], v[34:35], v[76:77] op_sel_hi:[1,0,1] neg_lo:[0,0,1] neg_hi:[0,0,1]
	v_pk_fma_f32 v[4:5], v[4:5], v[34:35], v[74:75] op_sel_hi:[1,0,1] neg_lo:[0,0,1] neg_hi:[0,0,1]
	v_pk_fma_f32 v[28:29], v[28:29], v[34:35], v[80:81] op_sel_hi:[1,0,1] neg_lo:[0,0,1] neg_hi:[0,0,1]
	v_pk_fma_f32 v[26:27], v[26:27], v[34:35], v[78:79] op_sel_hi:[1,0,1] neg_lo:[0,0,1] neg_hi:[0,0,1]
	v_pk_mul_f32 v[56:57], v[18:19], v[18:19]
	v_pk_mul_f32 v[54:55], v[20:21], v[20:21]
	v_pk_mul_f32 v[60:61], v[22:23], v[22:23]
	v_pk_mul_f32 v[58:59], v[24:25], v[24:25]
	v_pk_mul_f32 v[64:65], v[12:13], v[12:13]
	v_pk_mul_f32 v[62:63], v[14:15], v[14:15]
	v_pk_mul_f32 v[68:69], v[8:9], v[8:9]
	v_pk_mul_f32 v[66:67], v[10:11], v[10:11]
	v_pk_mul_f32 v[72:73], v[4:5], v[4:5]
	v_pk_mul_f32 v[70:71], v[6:7], v[6:7]
	v_pk_mul_f32 v[76:77], v[26:27], v[26:27]
	v_pk_mul_f32 v[74:75], v[28:29], v[28:29]
	v_pk_mul_f32 v[40:41], v[30:31], v[30:31]
	v_pk_mul_f32 v[42:43], v[32:33], v[32:33]
	v_pk_mul_f32 v[0:1], v[0:1], v[148:149]
	v_pk_mul_f32 v[2:3], v[2:3], v[150:151]
	v_cvt_pk_bf16_f32 v0, v0, v1
	v_cvt_pk_bf16_f32 v1, v2, v3
	global_store_dwordx2 v[82:83], v[0:1], off offset:224
	v_pk_mul_f32 v[48:49], v[52:53], v[52:53]
	v_pk_mul_f32 v[46:47], v[50:51], v[50:51]
	v_add_f32_e32 v34, v48, v49
	v_add_f32_e32 v34, v34, v46
	v_add_f32_e32 v34, v34, v47
	v_add_f32_e32 v34, v34, v56
	v_add_f32_e32 v34, v34, v57
	v_add_f32_e32 v34, v34, v54
	v_add_f32_e32 v34, v34, v55
	v_add_f32_e32 v34, v34, v60
	v_add_f32_e32 v34, v34, v61
	v_add_f32_e32 v34, v34, v58
	v_add_f32_e32 v34, v34, v59
	v_add_f32_e32 v34, v34, v64
	v_add_f32_e32 v34, v34, v65
	v_add_f32_e32 v34, v34, v62
	v_add_f32_e32 v34, v34, v63
	v_add_f32_e32 v34, v34, v68
	v_add_f32_e32 v34, v34, v69
	v_add_f32_e32 v34, v34, v66
	v_add_f32_e32 v34, v34, v67
	v_add_f32_e32 v34, v34, v72
	v_add_f32_e32 v34, v34, v73
	v_add_f32_e32 v34, v34, v70
	v_add_f32_e32 v34, v34, v71
	v_add_f32_e32 v34, v34, v76
	v_add_f32_e32 v34, v34, v77
	v_add_f32_e32 v34, v34, v74
	v_add_f32_e32 v34, v34, v75
	v_add_f32_e32 v34, v34, v40
	v_add_f32_e32 v34, v34, v41
	v_add_f32_e32 v34, v34, v42
	v_add_f32_e32 v34, v34, v43
	ds_bpermute_b32 v35, v35, v34
	s_waitcnt lgkmcnt(0)
	v_add_f32_e32 v34, v34, v35
	ds_bpermute_b32 v35, v39, v34
	s_waitcnt lgkmcnt(0)
	v_add_f32_e32 v34, v34, v35
	v_fmamk_f32 v34, v34, 0x3c000000, v241
	v_mul_f32_e32 v35, 0x4b800000, v34
	v_cmp_gt_f32_e32 vcc, s46, v34
	s_nop 1
	v_cndmask_b32_e32 v34, v34, v35, vcc
	v_rsq_f32_e32 v38, v34
	v_lshl_add_u64 v[34:35], v[36:37], 0, s[2:3]
	v_lshl_add_u64 v[36:37], v[34:35], 0, v[16:17]
	v_mul_f32_e32 v39, 0x45800000, v38
	v_cndmask_b32_e32 v38, v38, v39, vcc
	v_mul_f32_e32 v38, v84, v38
	v_pk_mul_f32 v[40:41], v[52:53], v[38:39] op_sel_hi:[1,0]
	v_pk_mul_f32 v[42:43], v[50:51], v[38:39] op_sel_hi:[1,0]
	v_pk_mul_f32 v[18:19], v[18:19], v[38:39] op_sel_hi:[1,0]
	v_pk_mul_f32 v[20:21], v[20:21], v[38:39] op_sel_hi:[1,0]
	v_pk_mul_f32 v[12:13], v[12:13], v[38:39] op_sel_hi:[1,0]
	v_pk_mul_f32 v[14:15], v[14:15], v[38:39] op_sel_hi:[1,0]
	v_pk_mul_f32 v[8:9], v[8:9], v[38:39] op_sel_hi:[1,0]
	v_pk_mul_f32 v[10:11], v[10:11], v[38:39] op_sel_hi:[1,0]
	v_pk_mul_f32 v[4:5], v[4:5], v[38:39] op_sel_hi:[1,0]
	v_pk_mul_f32 v[6:7], v[6:7], v[38:39] op_sel_hi:[1,0]
	v_pk_mul_f32 v[0:1], v[120:121], v[40:41]
	v_pk_mul_f32 v[2:3], v[122:123], v[42:43]
	v_cvt_pk_bf16_f32 v0, v0, v1
	v_cvt_pk_bf16_f32 v1, v2, v3
	global_store_dwordx2 v[36:37], v[0:1], off
	v_mov_b32_e32 v37, v17
	v_or_b32_e32 v36, 32, v16
	v_lshl_add_u64 v[36:37], v[34:35], 0, v[36:37]
	v_pk_mul_f32 v[0:1], v[124:125], v[18:19]
	v_pk_mul_f32 v[2:3], v[126:127], v[20:21]
	v_cvt_pk_bf16_f32 v0, v0, v1
	v_cvt_pk_bf16_f32 v1, v2, v3
	global_store_dwordx2 v[36:37], v[0:1], off
	v_pk_mul_f32 v[20:21], v[22:23], v[38:39] op_sel_hi:[1,0]
	v_pk_mul_f32 v[22:23], v[24:25], v[38:39] op_sel_hi:[1,0]
	v_mov_b32_e32 v19, v17
	v_or_b32_e32 v18, 64, v16
	v_lshl_add_u64 v[18:19], v[34:35], 0, v[18:19]
	v_pk_mul_f32 v[0:1], v[128:129], v[20:21]
	v_pk_mul_f32 v[2:3], v[22:23], v[130:131]
	v_cvt_pk_bf16_f32 v0, v0, v1
	v_cvt_pk_bf16_f32 v1, v2, v3
	global_store_dwordx2 v[18:19], v[0:1], off
	v_mov_b32_e32 v19, v17
	v_or_b32_e32 v18, 0x60, v16
	v_lshl_add_u64 v[18:19], v[34:35], 0, v[18:19]
	v_pk_mul_f32 v[0:1], v[12:13], v[132:133]
	v_pk_mul_f32 v[2:3], v[14:15], v[134:135]
	v_cvt_pk_bf16_f32 v0, v0, v1
	v_cvt_pk_bf16_f32 v1, v2, v3
	global_store_dwordx2 v[18:19], v[0:1], off
	v_mov_b32_e32 v13, v17
	v_or_b32_e32 v12, 0x80, v16
	v_lshl_add_u64 v[12:13], v[34:35], 0, v[12:13]
	v_pk_mul_f32 v[0:1], v[8:9], v[136:137]
	v_pk_mul_f32 v[2:3], v[10:11], v[138:139]
	v_cvt_pk_bf16_f32 v0, v0, v1
	v_cvt_pk_bf16_f32 v1, v2, v3
	global_store_dwordx2 v[12:13], v[0:1], off
	v_mov_b32_e32 v9, v17
	v_or_b32_e32 v8, 0xa0, v16
	v_lshl_add_u64 v[8:9], v[34:35], 0, v[8:9]
	v_pk_mul_f32 v[0:1], v[4:5], v[140:141]
	v_pk_mul_f32 v[2:3], v[6:7], v[142:143]
	v_cvt_pk_bf16_f32 v0, v0, v1
	v_cvt_pk_bf16_f32 v1, v2, v3
	global_store_dwordx2 v[8:9], v[0:1], off
	v_pk_mul_f32 v[6:7], v[26:27], v[38:39] op_sel_hi:[1,0]
	v_pk_mul_f32 v[8:9], v[28:29], v[38:39] op_sel_hi:[1,0]
	v_mov_b32_e32 v5, v17
	v_or_b32_e32 v4, 0xc0, v16
	v_lshl_add_u64 v[4:5], v[34:35], 0, v[4:5]
	v_or_b32_e32 v16, 0xe0, v16
	v_pk_mul_f32 v[0:1], v[6:7], v[144:145]
	v_pk_mul_f32 v[2:3], v[8:9], v[146:147]
	v_cvt_pk_bf16_f32 v0, v0, v1
	v_cvt_pk_bf16_f32 v1, v2, v3
	global_store_dwordx2 v[4:5], v[0:1], off
	v_pk_mul_f32 v[4:5], v[30:31], v[38:39] op_sel_hi:[1,0]
	v_pk_mul_f32 v[6:7], v[32:33], v[38:39] op_sel_hi:[1,0]
	v_pk_mul_f32 v[0:1], v[4:5], v[148:149]
	v_pk_mul_f32 v[2:3], v[6:7], v[150:151]
	v_cvt_pk_bf16_f32 v0, v0, v1
	v_cvt_pk_bf16_f32 v1, v2, v3
	v_lshl_add_u64 v[2:3], v[34:35], 0, v[16:17]
	global_store_dwordx2 v[2:3], v[0:1], off
